# v19 + the two flat barriers around attention poll one of eight replicated top counters (one per XCD group) instead of a single address
# baseline (speedup 1.0000x reference)
; __device__ __forceinline__ unsigned xb_ld(unsigned* p)              { return __hip_atomic_load(p, __ATOMIC_RELAXED, __HIP_MEMORY_SCOPE_AGENT); }
; __device__ __forceinline__ unsigned xb_add(unsigned* p, unsigned v) { return __hip_atomic_fetch_add(p, v, __ATOMIC_RELAXED, __HIP_MEMORY_SCOPE_AGENT); }
; #define XB_SPIN(cond, bar) do { unsigned _sp = 0; while (cond) { __builtin_amdgcn_s_sleep(1); \
;     if ((++_sp & 255u) == 0u) { if (xb_ld(&(bar)[XB_TMO])) break; if (_sp > XB_SPIN_CAP) { atomicAdd(&(bar)[XB_TMO], 1u); break; } } } } while (0)
; __device__ __forceinline__ void xcd_barrier(const XcdBarrier& b) {
;     asm volatile("s_waitcnt vmcnt(0)" ::: "memory");
;     __syncthreads();
;     if (threadIdx.x == 0) {
;         unsigned* bar = b.bar;
;         __builtin_amdgcn_s_waitcnt(0);
;         unsigned nloc = b.st[0], nx = b.st[1];
;         if (nloc == 0u) { xcd_barrier_complete(bar, b.x, nloc, nx); b.st[0] = nloc; b.st[1] = nx; }
;         const unsigned old = xb_add(&bar[XB_XSUB(b.x)], 1u);
;         const unsigned gen = old / nloc;
;         if (old + 1u == (gen + 1u) * nloc) {
;             __builtin_amdgcn_fence(__ATOMIC_RELEASE, "agent");
;             asm volatile("s_waitcnt vmcnt(0)" ::: "memory");
;             const unsigned og = xb_add(&bar[XB_TOP], 1u);
;             const unsigned tg = og / nx;
;             if (og + 1u == (tg + 1u) * nx) xb_add(&bar[XB_TOPGEN], 1u);
;             else XB_SPIN(xb_ld(&bar[XB_TOPGEN]) == tg, bar);
;             __builtin_amdgcn_fence(__ATOMIC_ACQUIRE, "agent");
;             xb_add(&bar[XB_XGEN(b.x)], 1u);
.Lgg6_f:
	global_atomic_add v251, v250, v252, s[54:55] offset:40 sc0
	v_mov_b32_e32 v0, 0
	v_mov_b32_e32 v47, 1
	global_atomic_add v47, v0, v47, s[10:11] sc0
	s_waitcnt vmcnt(0)
	v_readfirstlane_b32 s99, v251
	s_cmp_eq_u32 s99, 31
	s_cbranch_scc0 .Lgg6_n
	buffer_wbl2 sc1
	s_waitcnt vmcnt(0)
	v_mov_b32_e32 v253, 0xb200
	global_atomic_add v253, v252, s[54:55]
	global_atomic_add v253, v252, s[54:55] offset:64
	global_atomic_add v253, v252, s[54:55] offset:128
	global_atomic_add v253, v252, s[54:55] offset:192
	global_atomic_add v253, v252, s[54:55] offset:256
	global_atomic_add v253, v252, s[54:55] offset:320
	global_atomic_add v253, v252, s[54:55] offset:384
	global_atomic_add v253, v252, s[54:55] offset:448

; __device__ __forceinline__ unsigned xb_ld(unsigned* p)              { return __hip_atomic_load(p, __ATOMIC_RELAXED, __HIP_MEMORY_SCOPE_AGENT); }
; __device__ __forceinline__ unsigned xb_add(unsigned* p, unsigned v) { return __hip_atomic_fetch_add(p, v, __ATOMIC_RELAXED, __HIP_MEMORY_SCOPE_AGENT); }
; #define XB_SPIN(cond, bar) do { unsigned _sp = 0; while (cond) { __builtin_amdgcn_s_sleep(1); \
;     if ((++_sp & 255u) == 0u) { if (xb_ld(&(bar)[XB_TMO])) break; if (_sp > XB_SPIN_CAP) { atomicAdd(&(bar)[XB_TMO], 1u); break; } } } } while (0)
; __device__ __forceinline__ void xcd_barrier(const XcdBarrier& b) {
;     asm volatile("s_waitcnt vmcnt(0)" ::: "memory");
;     __syncthreads();
;     if (threadIdx.x == 0) {
;         unsigned* bar = b.bar;
;         __builtin_amdgcn_s_waitcnt(0);
;         unsigned nloc = b.st[0], nx = b.st[1];
;         if (nloc == 0u) { xcd_barrier_complete(bar, b.x, nloc, nx); b.st[0] = nloc; b.st[1] = nx; }
;         const unsigned old = xb_add(&bar[XB_XSUB(b.x)], 1u);
;         const unsigned gen = old / nloc;
;         if (old + 1u == (gen + 1u) * nloc) {
;             __builtin_amdgcn_fence(__ATOMIC_RELEASE, "agent");
;             asm volatile("s_waitcnt vmcnt(0)" ::: "memory");
;             const unsigned og = xb_add(&bar[XB_TOP], 1u);
;             const unsigned tg = og / nx;
;             if (og + 1u == (tg + 1u) * nx) xb_add(&bar[XB_TOPGEN], 1u);
;             else XB_SPIN(xb_ld(&bar[XB_TOPGEN]) == tg, bar);
;             __builtin_amdgcn_fence(__ATOMIC_ACQUIRE, "agent");
;             xb_add(&bar[XB_XGEN(b.x)], 1u);
;             asm volatile("s_waitcnt vmcnt(0)" ::: "memory");
;         } else {
;             XB_SPIN(xb_ld(&bar[XB_XGEN(b.x)]) == gen, bar);
;             __builtin_amdgcn_fence(__ATOMIC_ACQUIRE, "agent");
;             asm volatile("s_waitcnt vmcnt(0)" ::: "memory");
;         }
.LBB0_571:
	s_cmp_gt_i32 s43, 7
	s_setprio 0
	s_cselect_b64 s[4:5], -1, 0
	s_and_b64 s[6:7], s[16:17], s[4:5]
	s_andn2_b64 vcc, exec, s[6:7]
	s_cbranch_vccnz .LBB0_621
	s_waitcnt vmcnt(0)
	s_waitcnt vmcnt(0) lgkmcnt(0)
	s_barrier
	s_and_saveexec_b64 s[6:7], s[12:13]
	s_cbranch_execz .LBB0_620
	s_and_b32 s98, s2, 7
	s_lshl_b32 s98, s98, 6
	s_add_i32 s98, s98, 0xb200
	v_mov_b32_e32 v253, s98
	s_mov_b32 s99, 0

; __device__ __forceinline__ unsigned xb_ld(unsigned* p)              { return __hip_atomic_load(p, __ATOMIC_RELAXED, __HIP_MEMORY_SCOPE_AGENT); }
; __device__ __forceinline__ unsigned xb_add(unsigned* p, unsigned v) { return __hip_atomic_fetch_add(p, v, __ATOMIC_RELAXED, __HIP_MEMORY_SCOPE_AGENT); }
; #define XB_SPIN(cond, bar) do { unsigned _sp = 0; while (cond) { __builtin_amdgcn_s_sleep(1); \
;     if ((++_sp & 255u) == 0u) { if (xb_ld(&(bar)[XB_TMO])) break; if (_sp > XB_SPIN_CAP) { atomicAdd(&(bar)[XB_TMO], 1u); break; } } } } while (0)
; __device__ __forceinline__ void xcd_barrier(const XcdBarrier& b) {
;     asm volatile("s_waitcnt vmcnt(0)" ::: "memory");
;     __syncthreads();
;     if (threadIdx.x == 0) {
;         unsigned* bar = b.bar;
;         __builtin_amdgcn_s_waitcnt(0);
;         unsigned nloc = b.st[0], nx = b.st[1];
;         if (nloc == 0u) { xcd_barrier_complete(bar, b.x, nloc, nx); b.st[0] = nloc; b.st[1] = nx; }
;         const unsigned old = xb_add(&bar[XB_XSUB(b.x)], 1u);
;         const unsigned gen = old / nloc;
;         if (old + 1u == (gen + 1u) * nloc) {
;             __builtin_amdgcn_fence(__ATOMIC_RELEASE, "agent");
;             asm volatile("s_waitcnt vmcnt(0)" ::: "memory");
;             const unsigned og = xb_add(&bar[XB_TOP], 1u);
;             const unsigned tg = og / nx;
;             if (og + 1u == (tg + 1u) * nx) xb_add(&bar[XB_TOPGEN], 1u);
;             else XB_SPIN(xb_ld(&bar[XB_TOPGEN]) == tg, bar);
;             __builtin_amdgcn_fence(__ATOMIC_ACQUIRE, "agent");
;             xb_add(&bar[XB_XGEN(b.x)], 1u);
;             asm volatile("s_waitcnt vmcnt(0)" ::: "memory");
;         } else {
;             XB_SPIN(xb_ld(&bar[XB_XGEN(b.x)]) == gen, bar);
;             __builtin_amdgcn_fence(__ATOMIC_ACQUIRE, "agent");
;             asm volatile("s_waitcnt vmcnt(0)" ::: "memory");
;         }
.Lgg7_f:
	global_atomic_add v251, v250, v252, s[54:55] offset:44 sc0
	s_nop 0
	s_waitcnt vmcnt(0)
	v_readfirstlane_b32 s98, v251
	s_cmp_eq_u32 s98, 31
	s_cbranch_scc0 .Lgg7_n
	buffer_wbl2 sc1
	s_waitcnt vmcnt(0)
	v_mov_b32_e32 v253, 0xb400
	global_atomic_add v253, v252, s[54:55]
	global_atomic_add v253, v252, s[54:55] offset:64
	global_atomic_add v253, v252, s[54:55] offset:128
	global_atomic_add v253, v252, s[54:55] offset:192
	global_atomic_add v253, v252, s[54:55] offset:256
	global_atomic_add v253, v252, s[54:55] offset:320
	global_atomic_add v253, v252, s[54:55] offset:384
	global_atomic_add v253, v252, s[54:55] offset:448
.Lgg7_n:
	s_and_b32 s98, s2, 7
	s_lshl_b32 s98, s98, 6
	s_add_i32 s98, s98, 0xb400
	v_mov_b32_e32 v253, s98
	s_mov_b32 s99, 0
